# fox loop: original exp/PV instruction order with V fragments preloaded (instead of the interleaved rewrite)
# baseline (speedup 1.0000x reference)
; #define MFMA(a, b, c) __builtin_amdgcn_mfma_f32_32x32x16_f16(__builtin_bit_cast(h16x8, (a)), __builtin_bit_cast(h16x8, (b)), (c), 0, 0, 0)
; DI unsigned pk2(float a, float b) { f2_t v = {a, b}; bf2_t r = __builtin_convertvector(v, bf2_t); return __builtin_bit_cast(unsigned, r); }
; template <int MODE> ...
;     ...
;             const float mc = m[nb];
;             float ps = 0.f;
; #pragma unroll
;             for (int i = 0; i < 16; ++i) {
;               sv[i] = __builtin_amdgcn_exp2f(sv[i] - mc);
;               ps += sv[i];
;             }
;             l[nb] += ps;
; #pragma unroll
;             for (int s2 = 0; s2 < 2; ++s2) {
;               const unsigned u0 = pk2(sv[8 * s2], sv[8 * s2 + 1]), u1 = pk2(sv[8 * s2 + 2], sv[8 * s2 + 3]);
;               const unsigned u2 = pk2(sv[8 * s2 + 4], sv[8 * s2 + 5]), u3 = pk2(sv[8 * s2 + 6], sv[8 * s2 + 7]);
;               const uint4 uu = make_uint4(u0, u1, u2, u3);
;               pk[nb][s2] = __builtin_bit_cast(bf16x8, uu);
;             }
;           }
;         }
;         if (MODE != M_CMP2) {
; #pragma unroll
;           for (int s2 = 0; s2 < 2; ++s2) {
; #pragma unroll
;             for (int db = 0; db < 2; ++db) {
;               const u16* vp = Vt + (kb * 32 + 16 * s2 + 4 * h + q4) * LDK + db * 32 + 16 * blk + 4 * p4;
;               const s16x4 lo = __builtin_amdgcn_ds_read_tr16_b64_v4i16((__attribute__((address_space(3))) s16x4*)(vp));
;               const s16x4 hi = __builtin_amdgcn_ds_read_tr16_b64_v4i16((__attribute__((address_space(3))) s16x4*)(vp + 8 * LDK));
;               const bf16x8 a = __builtin_shufflevector(lo, hi, 0, 1, 2, 3, 4, 5, 6, 7);
;               O[db][0] = MFMA(a, pk[0][s2], O[db][0]);
;               O[db][1] = MFMA(a, pk[1][s2], O[db][1]);
;             }
;           }
;         }
.LBB0_647:
	v_or_b32_e32 v83, s22, v245
	v_mad_u32_u24 v83, v83, s76, v222
	ds_read_b64_tr_b16 v[84:85], v83 offset:18432
	ds_read_b64_tr_b16 v[86:87], v83 offset:19584
	ds_read_b64_tr_b16 v[88:89], v83 offset:18496
	ds_read_b64_tr_b16 v[90:91], v83 offset:19648
	ds_read_b64_tr_b16 v[92:93], v83 offset:20736
	ds_read_b64_tr_b16 v[94:95], v83 offset:21888
	ds_read_b64_tr_b16 v[96:97], v83 offset:20800
	ds_read_b64_tr_b16 v[98:99], v83 offset:21952
	v_sub_f32_e32 v2, v112, v219
	v_exp_f32_e32 v2, v2
	v_sub_f32_e32 v4, v113, v219
	v_exp_f32_e32 v4, v4
	v_sub_f32_e32 v5, v114, v219
	v_exp_f32_e32 v5, v5
	v_sub_f32_e32 v6, v115, v219
	v_exp_f32_e32 v6, v6
	v_sub_f32_e32 v7, v116, v219
	v_add_f32_e32 v3, 0, v2
	v_exp_f32_e32 v7, v7
	v_sub_f32_e32 v8, v117, v219
	v_add_f32_e32 v3, v4, v3
	v_exp_f32_e32 v8, v8
	v_sub_f32_e32 v9, v118, v219
	v_add_f32_e32 v3, v5, v3
	v_exp_f32_e32 v9, v9
	v_sub_f32_e32 v10, v119, v219
	v_add_f32_e32 v3, v6, v3
	v_exp_f32_e32 v13, v10
	v_sub_f32_e32 v10, v120, v219
	v_add_f32_e32 v3, v7, v3
	v_exp_f32_e32 v112, v10
	v_sub_f32_e32 v10, v121, v219
	v_add_f32_e32 v3, v8, v3
	v_exp_f32_e32 v113, v10
	v_sub_f32_e32 v10, v122, v219
	v_add_f32_e32 v3, v9, v3
	v_exp_f32_e32 v114, v10
	v_sub_f32_e32 v10, v123, v219
	v_add_f32_e32 v3, v13, v3
	v_exp_f32_e32 v115, v10
	v_sub_f32_e32 v10, v124, v219
	v_add_f32_e32 v3, v112, v3
	v_exp_f32_e32 v116, v10
	v_sub_f32_e32 v10, v125, v219
	v_add_f32_e32 v3, v113, v3
	v_exp_f32_e32 v117, v10
	v_sub_f32_e32 v10, v126, v219
	v_add_f32_e32 v3, v114, v3
	v_exp_f32_e32 v118, v10
	v_sub_f32_e32 v10, v127, v219
	v_add_f32_e32 v3, v115, v3
	v_exp_f32_e32 v119, v10
	v_cvt_pk_f16_f32 v11, v5, v6
	v_sub_f32_e32 v6, v128, v14
	v_add_f32_e32 v3, v116, v3
	v_cvt_pk_f16_f32 v12, v7, v8
	v_exp_f32_e32 v6, v6
	v_sub_f32_e32 v8, v129, v14
	v_add_f32_e32 v3, v117, v3
	v_cvt_pk_f16_f32 v13, v9, v13
	v_exp_f32_e32 v8, v8
	v_sub_f32_e32 v9, v130, v14
	v_add_f32_e32 v3, v118, v3
	v_cvt_pk_f16_f32 v10, v2, v4
	v_cvt_pk_f16_f32 v2, v112, v113
	v_exp_f32_e32 v9, v9
	v_sub_f32_e32 v112, v131, v14
	v_add_f32_e32 v3, v119, v3
	v_exp_f32_e32 v113, v112
	v_sub_f32_e32 v112, v132, v14
	v_add_f32_e32 v213, v208, v3
	v_cvt_pk_f16_f32 v3, v114, v115
	v_add_f32_e32 v7, 0, v6
	v_exp_f32_e32 v114, v112
	v_sub_f32_e32 v112, v133, v14
	v_add_f32_e32 v7, v8, v7
	v_exp_f32_e32 v115, v112
	v_sub_f32_e32 v112, v134, v14
	v_cvt_pk_f16_f32 v4, v116, v117
	v_add_f32_e32 v7, v9, v7
	v_exp_f32_e32 v116, v112
	v_sub_f32_e32 v112, v135, v14
	v_add_f32_e32 v7, v113, v7
	v_exp_f32_e32 v117, v112
	v_sub_f32_e32 v112, v136, v14
	v_cvt_pk_f16_f32 v5, v118, v119
	v_add_f32_e32 v7, v114, v7
	v_exp_f32_e32 v118, v112
	v_sub_f32_e32 v112, v137, v14
	v_add_f32_e32 v7, v115, v7
	v_exp_f32_e32 v119, v112
	v_sub_f32_e32 v112, v138, v14
	v_add_f32_e32 v7, v116, v7
	v_exp_f32_e32 v120, v112
	v_sub_f32_e32 v112, v139, v14
	v_add_f32_e32 v7, v117, v7
	v_exp_f32_e32 v121, v112
	v_sub_f32_e32 v112, v140, v14
	v_add_f32_e32 v7, v118, v7
	v_exp_f32_e32 v122, v112
	v_sub_f32_e32 v112, v141, v14
	v_add_f32_e32 v7, v119, v7
	v_exp_f32_e32 v123, v112
	v_sub_f32_e32 v112, v142, v14
	v_add_f32_e32 v7, v120, v7
	v_exp_f32_e32 v124, v112
	v_sub_f32_e32 v112, v143, v14
	v_add_f32_e32 v7, v121, v7
	v_exp_f32_e32 v125, v112
	v_add_f32_e32 v7, v122, v7
	v_add_f32_e32 v7, v123, v7
	v_add_f32_e32 v7, v124, v7
	v_add_f32_e32 v7, v125, v7
	v_cvt_pk_f16_f32 v114, v114, v115
	v_cvt_pk_f16_f32 v115, v116, v117
	v_or_b32_e32 v116, s22, v245
	v_add_f32_e32 v212, v212, v7
	v_cvt_pk_f16_f32 v7, v120, v121
	v_mad_u32_u24 v120, v116, s76, v222
	v_cvt_pk_f16_f32 v112, v6, v8
	v_cvt_pk_f16_f32 v6, v118, v119
	v_cvt_pk_f16_f32 v113, v9, v113
	s_waitcnt lgkmcnt(0)
	v_mfma_f32_32x32x16_f16 v[64:79], v[84:87], v[10:13], v[64:79]
	v_cvt_pk_f16_f32 v8, v122, v123
	v_cvt_pk_f16_f32 v9, v124, v125
	v_mov_b32_e32 v208, v213
	v_mfma_f32_32x32x16_f16 v[32:47], v[84:87], v[112:115], v[32:47]
	s_waitcnt lgkmcnt(0)
	v_mfma_f32_32x32x16_f16 v[48:63], v[88:91], v[10:13], v[48:63]
	v_mfma_f32_32x32x16_f16 v[16:31], v[88:91], v[112:115], v[16:31]
	s_waitcnt lgkmcnt(0)
	v_mfma_f32_32x32x16_f16 v[64:79], v[92:95], v[2:5], v[64:79]
	v_mfma_f32_32x32x16_f16 v[32:47], v[92:95], v[6:9], v[32:47]
	s_waitcnt lgkmcnt(0)
	v_mfma_f32_32x32x16_f16 v[48:63], v[96:99], v[2:5], v[48:63]
	v_mfma_f32_32x32x16_f16 v[16:31], v[96:99], v[6:9], v[16:31]
